# P1 EpiAct: row-scale partials staged to LDS by DMA in the K-loop, epilogue reads LDS instead of global
# speedup vs baseline: 1.0607x; 1.0607x over previous
; #define PG8_BAR __builtin_amdgcn_s_barrier()
; template <class Epi, class Sched, bool ALIGN_EPI = false, bool SP2 = false>
; __device__ __forceinline__ void gemm_phase(PG8_LAS unsigned char* lds, const Gemm g, const Sched& S, const Epi& E) {
;     int tid_ = threadIdx.x; asm volatile("" : "+v"(tid_));
;     const int tid = tid_, wid = __builtin_amdgcn_readfirstlane(tid >> 6), lane = tid & 63, wr = wid >> 2, wc = wid & 3, fr = lane & 15, fq = lane >> 4;
;     int K_ = g.K; asm volatile("" : "+s"(K_));
;     const int K = K_, nt = K / BK;
;     unsigned voffA[2], voffB[2];
; #pragma unroll
;     for (int i = 0; i < 2; ++i) { int R, C; stage_rc(tid * 16 + i * 8192, R, C); const int Rb = Epi::PERM ? ((R & ~31) + perm32(R & 31)) : R;
;         voffA[i] = (unsigned)(R * K + C) * 2u; voffB[i] = (unsigned)(Rb * K + C) * 2u; }
;     const size_t kstep = (size_t)(BK * 2);
;     const size_t hstep = (size_t)HALF * K * 2;
;     const size_t tstep = 2 * hstep;
;     const unsigned ldsw = (unsigned)wid * 1024u;
;     const int aoff = lds_byte(wr * 64 + fr, fq * 8), boff = lds_byte(wc * 32 + fr, fq * 8);
;     ...
;     Unit cur, nxt; int ui = 0;
;     if (!S.next(0, cur)) return;
;     f32x4 acc[2][2][4][2];
; #pragma unroll
;     for (int a = 0; a < 2; ++a)
; #pragma unroll
;         for (int b = 0; b < 2; ++b)
; #pragma unroll
;             for (int m = 0; m < 4; ++m)
; #pragma unroll
;                 for (int n = 0; n < 2; ++n) acc[a][b][m][n] = (f32x4){0.f, 0.f, 0.f, 0.f};
;     bf16x8 At[4][2], B0[2][2], B1[2][2];
;     const char* cA = (const char*)g.A + (size_t)cur.pm * tstep; const char* cB = (const char*)g.Bt + (size_t)cur.pn * tstep;
;     S.a_ready(cur);
;     if constexpr (SP2) {
;         PG8_STAGE(PG8_SB(0, 0), cB, voffB); PG8_STAGE(PG8_SB(0, 1), cB + hstep, voffB); PG8_STAGE(PG8_SA(0, 0), cA, voffA); PG8_STAGE(PG8_SA(0, 1), cA + hstep, voffA);
;         if (wr == 1) PG8_BAR;
;         PG8_WAIT_V(2); PG8_BAR;
;         PG8_STAGE(PG8_SB(1, 0), cB + kstep, voffB); PG8_STAGE(PG8_SA(1, 0), cA + kstep, voffA); PG8_STAGE(PG8_SB(1, 1), cB + hstep + kstep, voffB);
;         PG8_WAIT_V(6); PG8_BAR;
;     } else {
;         PG8_STAGE(PG8_SB(0, 0), cB, voffB); PG8_STAGE(PG8_SA(0, 0), cA, voffA); PG8_STAGE(PG8_SB(0, 1), cB + hstep, voffB); PG8_STAGE(PG8_SA(0, 1), cA + hstep, voffA);
;         if (wr == 1) PG8_BAR;
;         PG8_WAIT_V(4); PG8_BAR;
.LBB0_249:
	s_cmp_lt_i32 s28, 2
	s_cselect_b64 s[4:5], -1, 0
	s_add_u32 s52, s26, 0x2900000
	s_addc_u32 s53, s27, 0
	s_add_u32 s46, s26, 0x8680000
	s_addc_u32 s47, s27, 0
	s_cmpk_eq_i32 s30, 0x100
	s_cselect_b64 s[54:55], -1, 0
	s_cmpk_lg_i32 s30, 0x100
	s_cselect_b64 s[50:51], -1, 0
	s_and_b64 s[10:11], s[4:5], s[6:7]
	s_andn2_b64 vcc, exec, s[10:11]
	s_cbranch_vccnz .LBB0_291
	v_lshlrev_b32_e32 v236, 4, v192
	v_mov_b32_e32 v237, 0
	v_lshl_add_u64 v[236:237], s[44:45], 0, v[236:237]
	v_mov_b32_e32 v12, v192
	s_movk_i32 s6, 0x400
	v_readfirstlane_b32 s9, v12
	s_cmpk_gt_i32 s2, 0x5d7
	s_cbranch_scc1 .LBB0_271
	v_lshlrev_b32_e32 v0, 4, v12
	v_add_u32_e32 v1, 0x2000, v0
	v_ashrrev_i32_e32 v2, 31, v1
	v_lshrrev_b32_e32 v2, 22, v2
	v_add_u32_e32 v2, v1, v2
	v_ashrrev_i32_e32 v2, 10, v2
	v_mul_i32_i24_e32 v3, 0x400, v2
	v_sub_u32_e32 v1, v1, v3
	v_lshrrev_b32_e32 v3, 4, v1
	v_bitop3_b32 v1, v3, v1, 32 bitop3:0x6c
	v_ashrrev_i32_e32 v3, 31, v1
	v_lshrrev_b32_e32 v3, 26, v3
	v_add_u32_e32 v3, v1, v3
	v_lshlrev_b32_e32 v5, 3, v2
	v_ashrrev_i32_e32 v4, 6, v3
	v_and_b32_e32 v5, -16, v5
	v_lshlrev_b32_e32 v2, 5, v2
	v_add_u32_e32 v5, v4, v5
	v_and_b32_e32 v13, 32, v2
	v_and_b32_e32 v2, 0xc0, v3
	v_and_b32_e32 v4, 3, v4
	s_mov_b32 s4, 0x7fffffe0
	v_lshrrev_b32_e32 v6, 2, v5
	v_lshlrev_b32_e32 v7, 1, v5
	v_sub_u32_e32 v1, v1, v2
	v_mov_b32_e32 v2, 1
	v_and_or_b32 v4, v5, s4, v4
	v_and_b32_e32 v6, 4, v6
	v_and_b32_e32 v7, 24, v7
	v_ashrrev_i16_sdwa v1, v2, sext(v1) dst_sel:DWORD dst_unused:UNUSED_PAD src0_sel:DWORD src1_sel:BYTE_0
	v_or3_b32 v4, v4, v6, v7
	v_bfe_i32 v14, v1, 0, 16
	v_mul_lo_u32 v4, v4, s6
	v_add_u32_e32 v1, v13, v14
	v_mul_lo_u32 v15, v5, s6
	v_add_lshl_u32 v130, v4, v1, 1
	v_add_lshl_u32 v132, v1, v15, 1
	v_bfe_i32 v1, v12, 27, 1
	v_lshrrev_b32_e32 v1, 22, v1
	v_add_u32_e32 v1, v0, v1
	v_and_b32_e32 v1, 0xfffffc00, v1
	v_sub_u32_e32 v0, v0, v1
	v_lshrrev_b32_e32 v1, 4, v0
	v_ashrrev_i32_e32 v4, 31, v12
	v_bitop3_b32 v0, v1, v0, 32 bitop3:0x6c
	v_lshrrev_b32_e32 v4, 26, v4
	v_ashrrev_i32_e32 v1, 31, v0
	v_add_u32_e32 v4, v12, v4
	v_lshrrev_b32_e32 v1, 26, v1
	v_ashrrev_i32_e32 v4, 6, v4
	v_add_u32_e32 v1, v0, v1
	v_lshlrev_b32_e32 v5, 3, v4
	v_ashrrev_i32_e32 v3, 6, v1
	v_and_b32_e32 v5, -16, v5
	v_add_u32_e32 v5, v3, v5
	v_and_b32_e32 v3, 3, v3
	s_ashr_i32 s39, s2, 31
	v_and_or_b32 v3, v5, s4, v3
	s_lshr_b32 s4, s39, 29
	s_add_i32 s4, s2, s4
	s_ashr_i32 s20, s9, 6
	s_ashr_i32 s7, s6, 31
	s_ashr_i32 s5, s4, 3
	s_and_b32 s4, s4, -8
	s_ashr_i32 s21, s9, 8
	s_lshl_b64 s[12:13], s[6:7], 8
	s_lshl_b64 s[14:15], s[6:7], 9
	s_lshl_b32 s3, s20, 10
	s_sub_i32 s4, s2, s4
	s_cmp_lt_i32 s4, 0
	s_movk_i32 s49, 0xbc
	s_cselect_b32 s8, s49, 0xbb
	s_mul_i32 s4, s4, s8
	s_add_i32 s4, s4, s5
	s_mul_hi_i32 s5, s4, 0x2e8ba2e9
	s_lshr_b32 s8, s5, 31
	s_ashr_i32 s5, s5, 5
	v_and_b32_e32 v1, 0xc0, v1
	s_add_i32 s5, s5, s8
	v_lshrrev_b32_e32 v6, 2, v5
	v_lshlrev_b32_e32 v7, 1, v5
	v_sub_u32_e32 v0, v0, v1
	s_lshl_b32 s16, s5, 3
	v_and_b32_e32 v6, 4, v6
	v_and_b32_e32 v7, 24, v7
	v_lshlrev_b32_e32 v4, 5, v4
	v_ashrrev_i16_sdwa v0, v2, sext(v0) dst_sel:DWORD dst_unused:UNUSED_PAD src0_sel:DWORD src1_sel:BYTE_0
	s_sub_i32 s8, 0x44, s16
	s_mulk_i32 s5, 0xb0
	v_or3_b32 v3, v3, v6, v7
	v_and_b32_e32 v16, 32, v4
	v_bfe_i32 v17, v0, 0, 16
	s_min_u32 s17, s8, 8
	s_sub_i32 s18, s4, s5
	v_mul_lo_u32 v3, v3, s6
	v_add_u32_e32 v0, v16, v17
	s_sext_i32_i16 s4, s18
	v_cvt_f32_ubyte0_e32 v2, s17
	v_add_lshl_u32 v134, v3, v0, 1
	v_cvt_f32_i32_e32 v1, s4
	v_rcp_iflag_f32_e32 v3, v2
	v_mul_lo_u32 v18, v5, s6
	v_add_lshl_u32 v136, v0, v18, 1
	s_ashr_i32 s4, s4, 30
	v_mul_f32_e32 v0, v1, v3
	v_trunc_f32_e32 v0, v0
	v_fma_f32 v1, -v0, v2, v1
	v_cvt_i32_f32_e32 v0, v0
	s_or_b32 s8, s4, 1
	v_cmp_ge_f32_e64 s[4:5], |v1|, v2
	s_and_b64 s[4:5], s[4:5], exec
	s_cselect_b32 s4, s8, 0
	v_readfirstlane_b32 s5, v0
	s_add_i32 s8, s5, s4
	s_mul_i32 s4, s8, s17
	s_sub_i32 s4, s18, s4
	s_sext_i32_i16 s4, s4
	s_add_i32 s4, s16, s4
	s_ashr_i32 s5, s4, 31
	s_mul_i32 s5, s14, s5
	s_mul_hi_u32 s16, s14, s4
	s_add_i32 s5, s16, s5
	s_lshr_b64 s[16:17], s[6:7], 23
	s_mul_i32 s17, s16, s4
	s_bfe_i64 s[18:19], s[8:9], 0x100000
	s_add_i32 s5, s5, s17
	s_mul_i32 s17, s14, s19
	s_mul_hi_u32 s19, s14, s18
	s_add_i32 s17, s19, s17
	s_mul_i32 s16, s16, s18
	s_add_i32 s17, s17, s16
	s_mul_i32 s16, s14, s18
	s_add_u32 s42, s26, s16
	s_addc_u32 s43, s27, s17
	s_add_i32 s56, s3, 0
	s_add_i32 m0, s56, 0x10000
	s_mul_i32 s22, s14, s4
	global_load_lds_dwordx4 v134, s[42:43]
	s_add_i32 m0, s56, 0x12000
	s_add_u32 s16, s42, s12
	global_load_lds_dwordx4 v130, s[42:43]
	s_addc_u32 s17, s43, s13
	s_add_i32 m0, s56, 0x14000
	v_mov_b32_e32 v135, 0
	global_load_lds_dwordx4 v134, s[16:17]
	s_add_i32 m0, s56, 0x16000
	s_add_u32 s40, s34, s22
	s_addc_u32 s41, s35, s5
	s_add_i32 s57, s56, 0x2000
	global_load_lds_dwordx4 v130, s[16:17]
	s_mov_b32 m0, s56
	s_add_u32 s18, s40, s12
	global_load_lds_dwordx4 v136, s[40:41]
	s_mov_b32 m0, s57
	s_addc_u32 s19, s41, s13
	s_add_i32 s58, s56, 0x4000
	global_load_lds_dwordx4 v132, s[40:41]
	s_mov_b32 m0, s58
	s_add_i32 s59, s56, 0x6000
	global_load_lds_dwordx4 v136, s[18:19]
	s_mov_b32 m0, s59
	v_mov_b32_e32 v131, v135
	global_load_lds_dwordx4 v132, s[18:19]
	v_mov_b32_e32 v137, v135
	v_mov_b32_e32 v133, v135
	s_cmp_eq_u32 s21, 1
	s_mov_b32 s60, 0
	v_lshl_add_u64 v[8:9], s[42:43], 0, v[134:135]
	v_lshl_add_u64 v[4:5], s[42:43], 0, v[130:131]
	v_lshl_add_u64 v[2:3], s[16:17], 0, v[134:135]
	v_lshl_add_u64 v[0:1], s[16:17], 0, v[130:131]
	v_lshl_add_u64 v[6:7], s[40:41], 0, v[136:137]
	s_cselect_b64 s[16:17], -1, 0
	s_cmp_lg_u32 s21, 1
	v_lshl_add_u64 v[10:11], s[40:41], 0, v[132:133]
	s_cbranch_scc1 .LBB0_253
	s_barrier

; #define PG8_STAGE(bufoff, gbase, voff) do { _Pragma("unroll") for (int _i = 0; _i < 2; ++_i) \
;         __builtin_amdgcn_global_load_lds((const unsigned*)((const char*)(gbase) + (voff)[_i]), (PG8_LAS unsigned*)(lds + (bufoff) + ldsw + _i * 8192), 16, 0, 0); } while (0)
; #define PG8_LDA(dst, b, h) do { _Pragma("unroll") for (int m = 0; m < 4; ++m) _Pragma("unroll") for (int k = 0; k < 2; ++k) dst[m][k] = *(const PG8_LAS bf16x8*)(lds + PG8_SA(b, h) + aoff + m * 2048 + k * 1024); } while (0)
; #define PG8_LDB(dst, b, h) do { _Pragma("unroll") for (int n = 0; n < 2; ++n) _Pragma("unroll") for (int k = 0; k < 2; ++k) dst[n][k] = *(const PG8_LAS bf16x8*)(lds + PG8_SB(b, h) + boff + n * 2048 + k * 1024); } while (0)
; #define PG8_MMA(ai, bj, At, Bt) do { __builtin_amdgcn_s_setprio(1); _Pragma("unroll") for (int m = 0; m < 4; ++m) _Pragma("unroll") for (int n = 0; n < 2; ++n) _Pragma("unroll") for (int k = 0; k < 2; ++k) \
;         acc[ai][bj][m][n] = __builtin_amdgcn_mfma_f32_16x16x32_bf16(Bt[n][k], At[m][k], acc[ai][bj][m][n], 0, 0, 0); __builtin_amdgcn_s_setprio(0); } while (0)
; #define PG8_WAIT_V(n) asm volatile("s_waitcnt vmcnt(" #n ")" ::: "memory")
; #define PG8_WAIT_L(n) asm volatile("s_waitcnt lgkmcnt(" #n ")" ::: "memory")
; #define PG8_BAR __builtin_amdgcn_s_barrier()
; #define PG8_SCHED __builtin_amdgcn_sched_barrier(0)
; template <class Epi, class Sched, bool ALIGN_EPI = false, bool SP2 = false>
; __device__ __forceinline__ void gemm_phase(PG8_LAS unsigned char* lds, const Gemm g, const Sched& S, const Epi& E) {
;     ...
;             PG8_LDB(B0, 0, 0); PG8_LDB(B1, 0, 1); PG8_SCHED; PG8_LDA(At, 0, 0); PG8_STAGE(PG8_SA(1, 1), a1 + hstep, voffA);
;             PG8_WAIT_V(8); PG8_WAIT_L(0); PG8_BAR; PG8_MMA(0, 0, At, B0); PG8_MMA(0, 1, At, B1); PG8_BAR; PG8_SCHED;
;             PG8_LDA(At, 0, 1); PG8_STAGE(PG8_SB(0, 0), b2, voffB); PG8_STAGE(PG8_SB(0, 1), b2 + hstep, voffB); PG8_STAGE(PG8_SA(0, 0), a2, voffA);
.LBB0_264:
	ds_read_b128 v[148:151], v168
	ds_read_b128 v[152:155], v168 offset:1024
	ds_read_b128 v[156:159], v168 offset:2048
	ds_read_b128 v[160:163], v168 offset:3072
	ds_read_b128 v[174:177], v169
	ds_read_b128 v[178:181], v169 offset:1024
	ds_read_b128 v[182:185], v169 offset:2048
	ds_read_b128 v[186:189], v169 offset:3072
	s_add_i32 s71, s42, 2
	s_add_u32 s72, s40, 0x80
	s_addc_u32 s43, s41, 0
	s_cmp_eq_u32 s63, s42
	s_cselect_b32 s42, s8, s72
	s_cselect_b32 s43, s9, s43
	s_cselect_b32 s73, s37, s38
	s_cselect_b32 s72, s36, s33
	v_lshl_add_u64 v[164:165], s[40:41], 0, v[140:141]
	s_add_i32 m0, s56, 0xc000
	ds_read_b128 v[194:197], v170
	ds_read_b128 v[198:201], v170 offset:1024
	ds_read_b128 v[202:205], v170 offset:2048
	ds_read_b128 v[206:209], v170 offset:3072
	ds_read_b128 v[210:213], v170 offset:4096
	ds_read_b128 v[214:217], v170 offset:5120
	ds_read_b128 v[218:221], v170 offset:6144
	ds_read_b128 v[222:225], v170 offset:7168
	global_load_lds_dwordx4 v[164:165], off
	v_lshl_add_u64 v[164:165], s[40:41], 0, v[142:143]
	s_add_i32 m0, s56, 0xe000
	s_nop 0
	global_load_lds_dwordx4 v[164:165], off
	s_waitcnt vmcnt(8)
	s_waitcnt lgkmcnt(0)
	s_barrier
	s_setprio 1
	s_waitcnt lgkmcnt(0)
	v_mfma_f32_16x16x32_bf16 v[120:123], v[148:151], v[194:197], v[120:123]
	v_mfma_f32_16x16x32_bf16 v[116:119], v[156:159], v[194:197], v[116:119]
	v_mfma_f32_16x16x32_bf16 v[108:111], v[148:151], v[202:205], v[108:111]
	v_mfma_f32_16x16x32_bf16 v[100:103], v[156:159], v[202:205], v[100:103]
	v_mfma_f32_16x16x32_bf16 v[92:95], v[148:151], v[210:213], v[92:95]
	v_mfma_f32_16x16x32_bf16 v[84:87], v[156:159], v[210:213], v[84:87]
	v_mfma_f32_16x16x32_bf16 v[76:79], v[148:151], v[218:221], v[76:79]
	v_mfma_f32_16x16x32_bf16 v[68:71], v[156:159], v[218:221], v[68:71]
	v_mfma_f32_16x16x32_bf16 v[120:123], v[152:155], v[198:201], v[120:123]
	v_mfma_f32_16x16x32_bf16 v[116:119], v[160:163], v[198:201], v[116:119]
	v_mfma_f32_16x16x32_bf16 v[108:111], v[152:155], v[206:209], v[108:111]
	v_mfma_f32_16x16x32_bf16 v[100:103], v[160:163], v[206:209], v[100:103]
	v_mfma_f32_16x16x32_bf16 v[92:95], v[152:155], v[214:217], v[92:95]
	v_mfma_f32_16x16x32_bf16 v[84:87], v[160:163], v[214:217], v[84:87]
	v_mfma_f32_16x16x32_bf16 v[76:79], v[152:155], v[222:225], v[76:79]
	v_mfma_f32_16x16x32_bf16 v[68:71], v[160:163], v[222:225], v[68:71]
	s_setprio 0
	s_setprio 1
	v_mfma_f32_16x16x32_bf16 v[124:127], v[174:177], v[194:197], v[124:127]
	v_mfma_f32_16x16x32_bf16 v[112:115], v[182:185], v[194:197], v[112:115]
	v_mfma_f32_16x16x32_bf16 v[104:107], v[174:177], v[202:205], v[104:107]
	v_mfma_f32_16x16x32_bf16 v[96:99], v[182:185], v[202:205], v[96:99]
	v_mfma_f32_16x16x32_bf16 v[88:91], v[174:177], v[210:213], v[88:91]
	v_mfma_f32_16x16x32_bf16 v[80:83], v[182:185], v[210:213], v[80:83]
	v_mfma_f32_16x16x32_bf16 v[72:75], v[174:177], v[218:221], v[72:75]
	v_mfma_f32_16x16x32_bf16 v[64:67], v[182:185], v[218:221], v[64:67]
	v_mfma_f32_16x16x32_bf16 v[124:127], v[178:181], v[198:201], v[124:127]
	v_mfma_f32_16x16x32_bf16 v[112:115], v[186:189], v[198:201], v[112:115]
	v_mfma_f32_16x16x32_bf16 v[104:107], v[178:181], v[206:209], v[104:107]
	v_mfma_f32_16x16x32_bf16 v[96:99], v[186:189], v[206:209], v[96:99]
	v_mfma_f32_16x16x32_bf16 v[88:91], v[178:181], v[214:217], v[88:91]
	v_mfma_f32_16x16x32_bf16 v[80:83], v[186:189], v[214:217], v[80:83]
	v_mfma_f32_16x16x32_bf16 v[72:75], v[178:181], v[222:225], v[72:75]
	v_mfma_f32_16x16x32_bf16 v[64:67], v[186:189], v[222:225], v[64:67]
	s_setprio 0
	s_barrier
	s_add_i32 s74, s66, s3
	v_lshl_add_u64 v[164:165], s[72:73], 0, v[134:135]
	s_mov_b32 m0, s74
	ds_read_b128 v[194:197], v170 offset:16384
	ds_read_b128 v[198:201], v170 offset:17408
	ds_read_b128 v[202:205], v170 offset:18432
	ds_read_b128 v[206:209], v170 offset:19456
	ds_read_b128 v[210:213], v170 offset:20480
	ds_read_b128 v[214:217], v170 offset:21504
	ds_read_b128 v[218:221], v170 offset:22528
	ds_read_b128 v[222:225], v170 offset:23552
	global_load_lds_dwordx4 v[164:165], off
	s_add_i32 m0, s74, 0x2000
	v_lshl_add_u64 v[190:191], s[72:73], 0, v[130:131]
	s_add_u32 s72, s72, s12
	s_addc_u32 s73, s73, s13
	s_add_i32 s74, s67, s3
	global_load_lds_dwordx4 v[190:191], off
	v_lshl_add_u64 v[226:227], s[72:73], 0, v[134:135]
	s_mov_b32 m0, s74
	v_lshl_add_u64 v[228:229], s[72:73], 0, v[130:131]
	global_load_lds_dwordx4 v[226:227], off
	s_add_i32 m0, s74, 0x2000
	v_lshl_add_u64 v[230:231], s[42:43], 0, v[136:137]
	global_load_lds_dwordx4 v[228:229], off
	s_mov_b32 m0, s56
	v_lshl_add_u64 v[232:233], s[42:43], 0, v[132:133]
	global_load_lds_dwordx4 v[230:231], off
	s_mov_b32 m0, s57
	s_nop 0
	global_load_lds_dwordx4 v[232:233], off
	s_cmp_lg_u32 s71, 2
	s_cbranch_scc1 .Lss_p1_skip
	s_lshl_b32 s84, s4, 14
	s_mov_b32 s85, 0
	s_add_i32 m0, s56, 0x20000
	v_lshl_add_u64 v[238:239], v[236:237], 0, s[84:85]
	s_add_u32 s84, s84, 0x2000
	global_load_lds_dwordx4 v[238:239], off
	s_add_i32 m0, s56, 0x22000
	v_lshl_add_u64 v[238:239], v[236:237], 0, s[84:85]
	global_load_lds_dwordx4 v[238:239], off
; #define PG8_STAGE(bufoff, gbase, voff) do { _Pragma("unroll") for (int _i = 0; _i < 2; ++_i) \
;         __builtin_amdgcn_global_load_lds((const unsigned*)((const char*)(gbase) + (voff)[_i]), (PG8_LAS unsigned*)(lds + (bufoff) + ldsw + _i * 8192), 16, 0, 0); } while (0)
; #define PG8_LDA(dst, b, h) do { _Pragma("unroll") for (int m = 0; m < 4; ++m) _Pragma("unroll") for (int k = 0; k < 2; ++k) dst[m][k] = *(const PG8_LAS bf16x8*)(lds + PG8_SA(b, h) + aoff + m * 2048 + k * 1024); } while (0)
; #define PG8_LDB(dst, b, h) do { _Pragma("unroll") for (int n = 0; n < 2; ++n) _Pragma("unroll") for (int k = 0; k < 2; ++k) dst[n][k] = *(const PG8_LAS bf16x8*)(lds + PG8_SB(b, h) + boff + n * 2048 + k * 1024); } while (0)
; #define PG8_MMA(ai, bj, At, Bt) do { __builtin_amdgcn_s_setprio(1); _Pragma("unroll") for (int m = 0; m < 4; ++m) _Pragma("unroll") for (int n = 0; n < 2; ++n) _Pragma("unroll") for (int k = 0; k < 2; ++k) \
;         acc[ai][bj][m][n] = __builtin_amdgcn_mfma_f32_16x16x32_bf16(Bt[n][k], At[m][k], acc[ai][bj][m][n], 0, 0, 0); __builtin_amdgcn_s_setprio(0); } while (0)
; #define PG8_WAIT_V(n) asm volatile("s_waitcnt vmcnt(" #n ")" ::: "memory")
; #define PG8_WAIT_L(n) asm volatile("s_waitcnt lgkmcnt(" #n ")" ::: "memory")
; #define PG8_BAR __builtin_amdgcn_s_barrier()
; #define PG8_SCHED __builtin_amdgcn_sched_barrier(0)
; template <class Epi, class Sched, bool ALIGN_EPI = false, bool SP2 = false>
; __device__ __forceinline__ void gemm_phase(PG8_LAS unsigned char* lds, const Gemm g, const Sched& S, const Epi& E) {
;     ...
;             PG8_WAIT_V(8); PG8_WAIT_L(0); PG8_BAR; PG8_MMA(1, 0, At, B0); PG8_MMA(1, 1, At, B1); PG8_BAR; PG8_SCHED;
;             PG8_LDB(B0, 1, 0); PG8_LDB(B1, 1, 1); PG8_SCHED; PG8_LDA(At, 1, 0); PG8_STAGE(PG8_SA(0, 1), a2 + hstep, voffA);
;             PG8_WAIT_V(8); PG8_WAIT_L(0); PG8_BAR; PG8_MMA(0, 0, At, B0); PG8_MMA(0, 1, At, B1); PG8_BAR; PG8_SCHED;
.Lss_p1_skip:
	s_waitcnt vmcnt(8)
	s_waitcnt lgkmcnt(0)
	s_barrier
	s_setprio 1
	s_waitcnt lgkmcnt(0)
	v_mfma_f32_16x16x32_bf16 v[60:63], v[148:151], v[194:197], v[60:63]
	v_mfma_f32_16x16x32_bf16 v[52:55], v[156:159], v[194:197], v[52:55]
	v_mfma_f32_16x16x32_bf16 v[44:47], v[148:151], v[202:205], v[44:47]
	v_mfma_f32_16x16x32_bf16 v[36:39], v[156:159], v[202:205], v[36:39]
	v_mfma_f32_16x16x32_bf16 v[28:31], v[148:151], v[210:213], v[28:31]
	v_mfma_f32_16x16x32_bf16 v[20:23], v[156:159], v[210:213], v[20:23]
	v_mfma_f32_16x16x32_bf16 v[12:15], v[148:151], v[218:221], v[12:15]
	v_mfma_f32_16x16x32_bf16 v[4:7], v[156:159], v[218:221], v[4:7]
	v_mfma_f32_16x16x32_bf16 v[60:63], v[152:155], v[198:201], v[60:63]
	v_mfma_f32_16x16x32_bf16 v[52:55], v[160:163], v[198:201], v[52:55]
	v_mfma_f32_16x16x32_bf16 v[44:47], v[152:155], v[206:209], v[44:47]
	v_mfma_f32_16x16x32_bf16 v[36:39], v[160:163], v[206:209], v[36:39]
	v_mfma_f32_16x16x32_bf16 v[28:31], v[152:155], v[214:217], v[28:31]
	v_mfma_f32_16x16x32_bf16 v[20:23], v[160:163], v[214:217], v[20:23]
	v_mfma_f32_16x16x32_bf16 v[12:15], v[152:155], v[222:225], v[12:15]
	v_mfma_f32_16x16x32_bf16 v[4:7], v[160:163], v[222:225], v[4:7]
	s_setprio 0
	s_setprio 1
	v_mfma_f32_16x16x32_bf16 v[56:59], v[174:177], v[194:197], v[56:59]
	v_mfma_f32_16x16x32_bf16 v[48:51], v[182:185], v[194:197], v[48:51]
	v_mfma_f32_16x16x32_bf16 v[40:43], v[174:177], v[202:205], v[40:43]
	v_mfma_f32_16x16x32_bf16 v[32:35], v[182:185], v[202:205], v[32:35]
	v_mfma_f32_16x16x32_bf16 v[24:27], v[174:177], v[210:213], v[24:27]
	v_mfma_f32_16x16x32_bf16 v[16:19], v[182:185], v[210:213], v[16:19]
	v_mfma_f32_16x16x32_bf16 v[8:11], v[174:177], v[218:221], v[8:11]
	v_mfma_f32_16x16x32_bf16 v[0:3], v[182:185], v[218:221], v[0:3]
	v_mfma_f32_16x16x32_bf16 v[56:59], v[178:181], v[198:201], v[56:59]
	v_mfma_f32_16x16x32_bf16 v[48:51], v[186:189], v[198:201], v[48:51]
	v_mfma_f32_16x16x32_bf16 v[40:43], v[178:181], v[206:209], v[40:43]
	v_mfma_f32_16x16x32_bf16 v[32:35], v[186:189], v[206:209], v[32:35]
	v_mfma_f32_16x16x32_bf16 v[24:27], v[178:181], v[214:217], v[24:27]
	v_mfma_f32_16x16x32_bf16 v[16:19], v[186:189], v[214:217], v[16:19]
	v_mfma_f32_16x16x32_bf16 v[8:11], v[178:181], v[222:225], v[8:11]
	v_mfma_f32_16x16x32_bf16 v[0:3], v[186:189], v[222:225], v[0:3]
	s_setprio 0
	s_barrier
	s_add_i32 s72, 0, 0x18000
	v_add_u32_e32 v128, s72, v166
	s_add_i32 s73, 0, 0x1c000
	ds_read_b128 v[148:151], v128
	ds_read_b128 v[152:155], v128 offset:1024
	ds_read_b128 v[156:159], v128 offset:2048
	ds_read_b128 v[160:163], v128 offset:3072
	v_add_u32_e32 v128, s73, v166
	ds_read_b128 v[174:177], v128
	ds_read_b128 v[178:181], v128 offset:1024
	ds_read_b128 v[182:185], v128 offset:2048
	ds_read_b128 v[186:189], v128 offset:3072
	s_add_u32 s42, s42, s12
	s_addc_u32 s43, s43, s13
	s_mov_b32 m0, s58
	v_lshl_add_u64 v[234:235], s[42:43], 0, v[136:137]
	ds_read_b128 v[194:197], v170 offset:32768
	ds_read_b128 v[198:201], v170 offset:33792
	ds_read_b128 v[202:205], v170 offset:34816
	ds_read_b128 v[206:209], v170 offset:35840
	ds_read_b128 v[210:213], v170 offset:36864
	ds_read_b128 v[214:217], v170 offset:37888
	ds_read_b128 v[218:221], v170 offset:38912
	ds_read_b128 v[222:225], v170 offset:39936
	global_load_lds_dwordx4 v[234:235], off
	v_lshl_add_u64 v[234:235], s[42:43], 0, v[132:133]
	s_mov_b32 m0, s59
	s_nop 0
	global_load_lds_dwordx4 v[234:235], off
	s_waitcnt vmcnt(8)
	s_waitcnt lgkmcnt(0)
	s_barrier
	s_setprio 1
	s_waitcnt lgkmcnt(0)
	v_mfma_f32_16x16x32_bf16 v[120:123], v[148:151], v[194:197], v[120:123]
	v_mfma_f32_16x16x32_bf16 v[116:119], v[156:159], v[194:197], v[116:119]
	v_mfma_f32_16x16x32_bf16 v[108:111], v[148:151], v[202:205], v[108:111]
	v_mfma_f32_16x16x32_bf16 v[100:103], v[156:159], v[202:205], v[100:103]
	v_mfma_f32_16x16x32_bf16 v[92:95], v[148:151], v[210:213], v[92:95]
	v_mfma_f32_16x16x32_bf16 v[84:87], v[156:159], v[210:213], v[84:87]
	v_mfma_f32_16x16x32_bf16 v[76:79], v[148:151], v[218:221], v[76:79]
	v_mfma_f32_16x16x32_bf16 v[68:71], v[156:159], v[218:221], v[68:71]
	v_mfma_f32_16x16x32_bf16 v[120:123], v[152:155], v[198:201], v[120:123]
	v_mfma_f32_16x16x32_bf16 v[116:119], v[160:163], v[198:201], v[116:119]
	v_mfma_f32_16x16x32_bf16 v[108:111], v[152:155], v[206:209], v[108:111]
	v_mfma_f32_16x16x32_bf16 v[100:103], v[160:163], v[206:209], v[100:103]
	v_mfma_f32_16x16x32_bf16 v[92:95], v[152:155], v[214:217], v[92:95]
	v_mfma_f32_16x16x32_bf16 v[84:87], v[160:163], v[214:217], v[84:87]
	v_mfma_f32_16x16x32_bf16 v[76:79], v[152:155], v[222:225], v[76:79]
	v_mfma_f32_16x16x32_bf16 v[68:71], v[160:163], v[222:225], v[68:71]
	s_setprio 0
	s_setprio 1
	v_mfma_f32_16x16x32_bf16 v[124:127], v[174:177], v[194:197], v[124:127]
	v_mfma_f32_16x16x32_bf16 v[112:115], v[182:185], v[194:197], v[112:115]
	v_mfma_f32_16x16x32_bf16 v[104:107], v[174:177], v[202:205], v[104:107]
	v_mfma_f32_16x16x32_bf16 v[96:99], v[182:185], v[202:205], v[96:99]
	v_mfma_f32_16x16x32_bf16 v[88:91], v[174:177], v[210:213], v[88:91]
	v_mfma_f32_16x16x32_bf16 v[80:83], v[182:185], v[210:213], v[80:83]
	v_mfma_f32_16x16x32_bf16 v[72:75], v[174:177], v[218:221], v[72:75]
	v_mfma_f32_16x16x32_bf16 v[64:67], v[182:185], v[218:221], v[64:67]
	v_mfma_f32_16x16x32_bf16 v[124:127], v[178:181], v[198:201], v[124:127]
	v_mfma_f32_16x16x32_bf16 v[112:115], v[186:189], v[198:201], v[112:115]
	v_mfma_f32_16x16x32_bf16 v[104:107], v[178:181], v[206:209], v[104:107]
	v_mfma_f32_16x16x32_bf16 v[96:99], v[186:189], v[206:209], v[96:99]
	v_mfma_f32_16x16x32_bf16 v[88:91], v[178:181], v[214:217], v[88:91]
	v_mfma_f32_16x16x32_bf16 v[80:83], v[186:189], v[214:217], v[80:83]
	v_mfma_f32_16x16x32_bf16 v[72:75], v[178:181], v[222:225], v[72:75]
	v_mfma_f32_16x16x32_bf16 v[64:67], v[186:189], v[222:225], v[64:67]
	s_setprio 0
	s_barrier
; #define PG8_STAGE(bufoff, gbase, voff) do { _Pragma("unroll") for (int _i = 0; _i < 2; ++_i) \
;         __builtin_amdgcn_global_load_lds((const unsigned*)((const char*)(gbase) + (voff)[_i]), (PG8_LAS unsigned*)(lds + (bufoff) + ldsw + _i * 8192), 16, 0, 0); } while (0)
; #define PG8_LDA(dst, b, h) do { _Pragma("unroll") for (int m = 0; m < 4; ++m) _Pragma("unroll") for (int k = 0; k < 2; ++k) dst[m][k] = *(const PG8_LAS bf16x8*)(lds + PG8_SA(b, h) + aoff + m * 2048 + k * 1024); } while (0)
; #define PG8_MMA(ai, bj, At, Bt) do { __builtin_amdgcn_s_setprio(1); _Pragma("unroll") for (int m = 0; m < 4; ++m) _Pragma("unroll") for (int n = 0; n < 2; ++n) _Pragma("unroll") for (int k = 0; k < 2; ++k) \
;         acc[ai][bj][m][n] = __builtin_amdgcn_mfma_f32_16x16x32_bf16(Bt[n][k], At[m][k], acc[ai][bj][m][n], 0, 0, 0); __builtin_amdgcn_s_setprio(0); } while (0)
; #define PG8_WAIT_V(n) asm volatile("s_waitcnt vmcnt(" #n ")" ::: "memory")
; #define PG8_WAIT_L(n) asm volatile("s_waitcnt lgkmcnt(" #n ")" ::: "memory")
; #define PG8_BAR __builtin_amdgcn_s_barrier()
; #define PG8_SCHED __builtin_amdgcn_sched_barrier(0)
; template <class Epi, class Sched, bool ALIGN_EPI = false, bool SP2 = false>
; __device__ __forceinline__ void gemm_phase(PG8_LAS unsigned char* lds, const Gemm g, const Sched& S, const Epi& E) {
;     ...
;         for (int t = 0; t < nt; t += 2) {
;     ...
;             PG8_LDA(At, 1, 1); PG8_STAGE(PG8_SB(1, 0), b3, voffB); PG8_STAGE(PG8_SB(1, 1), b3 + hstep, voffB); PG8_STAGE(PG8_SA(1, 0), a3, voffA);
;             PG8_WAIT_V(8); PG8_WAIT_L(0); PG8_BAR; PG8_MMA(1, 0, At, B0); PG8_MMA(1, 1, At, B1); PG8_BAR; PG8_SCHED;
	s_add_i32 s42, s72, s3
	v_lshl_add_u64 v[164:165], v[164:165], 0, s[18:19]
	s_mov_b32 m0, s42
	ds_read_b128 v[194:197], v170 offset:49152
	ds_read_b128 v[198:201], v170 offset:50176
	ds_read_b128 v[202:205], v170 offset:51200
	ds_read_b128 v[206:209], v170 offset:52224
	ds_read_b128 v[210:213], v170 offset:53248
	ds_read_b128 v[214:217], v170 offset:54272
	ds_read_b128 v[218:221], v170 offset:55296
	ds_read_b128 v[222:225], v170 offset:56320
	global_load_lds_dwordx4 v[164:165], off
	v_lshl_add_u64 v[164:165], v[190:191], 0, s[18:19]
	s_add_i32 m0, s42, 0x2000
	s_add_i32 s42, s73, s3
	global_load_lds_dwordx4 v[164:165], off
	v_lshl_add_u64 v[164:165], v[226:227], 0, s[18:19]
	s_mov_b32 m0, s42
	s_nop 0
	global_load_lds_dwordx4 v[164:165], off
	v_lshl_add_u64 v[164:165], v[228:229], 0, s[18:19]
	s_add_i32 m0, s42, 0x2000
	s_nop 0
	global_load_lds_dwordx4 v[164:165], off
	v_lshl_add_u64 v[164:165], v[230:231], 0, s[18:19]
	s_mov_b32 m0, s48
	s_nop 0
	global_load_lds_dwordx4 v[164:165], off
	v_lshl_add_u64 v[164:165], v[232:233], 0, s[18:19]
	s_mov_b32 m0, s61
	s_nop 0
	global_load_lds_dwordx4 v[164:165], off
	s_waitcnt vmcnt(8)
	s_waitcnt lgkmcnt(0)
	s_barrier
	s_setprio 1
	s_waitcnt lgkmcnt(0)
	v_mfma_f32_16x16x32_bf16 v[60:63], v[148:151], v[194:197], v[60:63]
	v_mfma_f32_16x16x32_bf16 v[52:55], v[156:159], v[194:197], v[52:55]
	v_mfma_f32_16x16x32_bf16 v[44:47], v[148:151], v[202:205], v[44:47]
	v_mfma_f32_16x16x32_bf16 v[36:39], v[156:159], v[202:205], v[36:39]
	v_mfma_f32_16x16x32_bf16 v[28:31], v[148:151], v[210:213], v[28:31]
	v_mfma_f32_16x16x32_bf16 v[20:23], v[156:159], v[210:213], v[20:23]
	v_mfma_f32_16x16x32_bf16 v[12:15], v[148:151], v[218:221], v[12:15]
	v_mfma_f32_16x16x32_bf16 v[4:7], v[156:159], v[218:221], v[4:7]
	v_mfma_f32_16x16x32_bf16 v[60:63], v[152:155], v[198:201], v[60:63]
	v_mfma_f32_16x16x32_bf16 v[52:55], v[160:163], v[198:201], v[52:55]
	v_mfma_f32_16x16x32_bf16 v[44:47], v[152:155], v[206:209], v[44:47]
	v_mfma_f32_16x16x32_bf16 v[36:39], v[160:163], v[206:209], v[36:39]
	v_mfma_f32_16x16x32_bf16 v[28:31], v[152:155], v[214:217], v[28:31]
	v_mfma_f32_16x16x32_bf16 v[20:23], v[160:163], v[214:217], v[20:23]
	v_mfma_f32_16x16x32_bf16 v[12:15], v[152:155], v[222:225], v[12:15]
	v_mfma_f32_16x16x32_bf16 v[4:7], v[160:163], v[222:225], v[4:7]
	s_setprio 0
	s_setprio 1
	v_mfma_f32_16x16x32_bf16 v[56:59], v[174:177], v[194:197], v[56:59]
	v_mfma_f32_16x16x32_bf16 v[48:51], v[182:185], v[194:197], v[48:51]
	v_mfma_f32_16x16x32_bf16 v[40:43], v[174:177], v[202:205], v[40:43]
	v_mfma_f32_16x16x32_bf16 v[32:35], v[182:185], v[202:205], v[32:35]
	v_mfma_f32_16x16x32_bf16 v[24:27], v[174:177], v[210:213], v[24:27]
	v_mfma_f32_16x16x32_bf16 v[16:19], v[182:185], v[210:213], v[16:19]
	v_mfma_f32_16x16x32_bf16 v[8:11], v[174:177], v[218:221], v[8:11]
	v_mfma_f32_16x16x32_bf16 v[0:3], v[182:185], v[218:221], v[0:3]
	v_mfma_f32_16x16x32_bf16 v[56:59], v[178:181], v[198:201], v[56:59]
	v_mfma_f32_16x16x32_bf16 v[48:51], v[186:189], v[198:201], v[48:51]
	v_mfma_f32_16x16x32_bf16 v[40:43], v[178:181], v[206:209], v[40:43]
	v_mfma_f32_16x16x32_bf16 v[32:35], v[186:189], v[206:209], v[32:35]
	v_mfma_f32_16x16x32_bf16 v[24:27], v[178:181], v[214:217], v[24:27]
	v_mfma_f32_16x16x32_bf16 v[16:19], v[186:189], v[214:217], v[16:19]
	v_mfma_f32_16x16x32_bf16 v[8:11], v[178:181], v[222:225], v[8:11]
	v_mfma_f32_16x16x32_bf16 v[0:3], v[186:189], v[222:225], v[0:3]
	s_setprio 0
	s_barrier
	s_add_u32 s40, s40, 0x100
	s_addc_u32 s41, s41, 0
	s_add_u32 s33, s33, 0x100
	s_addc_u32 s38, s38, 0
	s_cmp_ge_i32 s71, s62
	s_mov_b32 s42, s71
	s_cbranch_scc0 .LBB0_264

; __device__ __forceinline__ void row_rs8(const float* SS, int row0, int fq, float (&rsv)[2][4]) {
;     f32x4 q[2][4];
; #pragma unroll
;     for (int ai = 0; ai < 2; ++ai)
; #pragma unroll
;         for (int m = 0; m < 4; ++m) q[ai][m] = *(const f32x4*)(SS + (size_t)(row0 + ai * HALF + m * 16) * 16 + 4 * fq);
; #pragma unroll
;     for (int ai = 0; ai < 2; ++ai)
; #pragma unroll
;         for (int m = 0; m < 4; ++m) { float t = (q[ai][m][0] + q[ai][m][1]) + (q[ai][m][2] + q[ai][m][3]); t += __shfl_xor(t, 16); t += __shfl_xor(t, 32); rsv[ai][m] = __builtin_amdgcn_rsqf(t * (1.0f / 1024.0f) + 1e-6f); }
; }
;     __device__ __forceinline__ void operator()(const f32x4 (&acc)[2][2][4][2], const Unit& u, int wr, int wc, int fr, int fq) const {
;         const int row0 = u.pm * BM + wr * 64 + fr, col0 = u.pn * HALF + wc * 32 + 8 * fq;
;         float rsv[2][4]; row_rs8(SS, row0, fq, rsv);
.LBB0_267:
	v_lshl_add_u32 v162, s4, 8, v129
	v_and_b32_e32 v128, 48, v192
	v_or_b32_e32 v160, 16, v162
	v_lshl_add_u32 v128, v129, 6, v128
	v_or_b32_e32 v158, 32, v162
	v_add_u32_e32 v128, 0x20000, v128
	v_or_b32_e32 v156, 48, v162
	ds_read_b128 v[174:177], v128
	ds_read_b128 v[178:181], v128 offset:1024
	ds_read_b128 v[182:185], v128 offset:2048
	ds_read_b128 v[186:189], v128 offset:3072
	ds_read_b128 v[194:197], v128 offset:8192
	ds_read_b128 v[198:201], v128 offset:9216
	ds_read_b128 v[202:205], v128 offset:10240
	ds_read_b128 v[206:209], v128 offset:11264
	v_add_u32_e32 v154, 0x80, v162
	v_add_u32_e32 v152, 0x90, v162
	v_add_u32_e32 v150, 0xa0, v162
	v_add_u32_e32 v148, 0xb0, v162
	v_and_b32_e32 v149, 64, v171
	v_xor_b32_e32 v128, 16, v171
	v_add_u32_e32 v149, 64, v149
	v_xor_b32_e32 v151, 32, v171
	v_cmp_lt_i32_e32 vcc, v128, v149
	v_mul_f32_e32 v124, v124, v120
	v_mul_f32_e32 v125, v125, v121
	v_cndmask_b32_e32 v128, v171, v128, vcc
	v_cmp_lt_i32_e32 vcc, v151, v149
	v_lshlrev_b32_e32 v128, 2, v128
	v_mul_f32_e32 v126, v126, v122
	v_cndmask_b32_e32 v149, v171, v151, vcc
	v_lshlrev_b32_e32 v149, 2, v149
	v_mul_f32_e32 v127, v127, v123
	v_mul_f32_e32 v115, v115, v119
	v_lshl_or_b32 v164, s5, 7, v167
	s_and_b64 vcc, exec, s[6:7]
	s_mov_b64 s[6:7], -1
	s_waitcnt lgkmcnt(0)
	v_mov_b32_e32 v190, v175
	v_mov_b32_e32 v191, v176
	v_mov_b32_e32 v175, v177
	v_pk_add_f32 v[174:175], v[190:191], v[174:175]
	v_mov_b32_e32 v176, v179
	v_mov_b32_e32 v177, v180
	v_mov_b32_e32 v179, v181
	v_add_f32_e32 v151, v174, v175
	v_mov_b32_e32 v180, v183
	v_mov_b32_e32 v181, v184
	v_mov_b32_e32 v183, v185
	v_mov_b32_e32 v184, v187
	v_mov_b32_e32 v185, v188
	v_mov_b32_e32 v187, v189
	v_mov_b32_e32 v188, v195
	v_mov_b32_e32 v189, v196
	v_mov_b32_e32 v195, v197
	v_pk_add_f32 v[174:175], v[176:177], v[178:179]
	v_pk_add_f32 v[176:177], v[180:181], v[182:183]
	v_pk_add_f32 v[180:181], v[188:189], v[194:195]
	ds_bpermute_b32 v153, v128, v151
	v_add_f32_e32 v155, v174, v175
	v_pk_add_f32 v[178:179], v[184:185], v[186:187]
	v_add_f32_e32 v157, v176, v177
	v_add_f32_e32 v161, v180, v181
	ds_bpermute_b32 v163, v128, v155
	v_add_f32_e32 v159, v178, v179
	ds_bpermute_b32 v165, v128, v157
	ds_bpermute_b32 v174, v128, v161
	ds_bpermute_b32 v173, v128, v159
	s_waitcnt lgkmcnt(4)
	v_add_f32_e32 v151, v151, v153
	ds_bpermute_b32 v153, v149, v151
	s_waitcnt lgkmcnt(4)
	v_add_f32_e32 v155, v155, v163
	s_waitcnt lgkmcnt(3)
	v_add_f32_e32 v157, v157, v165
	s_waitcnt lgkmcnt(2)
	v_add_f32_e32 v165, v161, v174
	ds_bpermute_b32 v161, v149, v155
	s_waitcnt lgkmcnt(2)
	v_add_f32_e32 v159, v159, v173
	ds_bpermute_b32 v163, v149, v157
	ds_bpermute_b32 v173, v149, v159
	ds_bpermute_b32 v174, v149, v165
	s_waitcnt lgkmcnt(4)
	v_add_f32_e32 v151, v151, v153
	v_fmamk_f32 v151, v151, 0x3a800000, v172
	s_waitcnt lgkmcnt(3)
	v_add_f32_e32 v153, v155, v161
	v_mov_b32_e32 v176, v199
	v_mov_b32_e32 v177, v200
	v_mov_b32_e32 v199, v201
	s_waitcnt lgkmcnt(2)
	v_add_f32_e32 v155, v157, v163
	v_rsq_f32_e32 v175, v151
	v_fmamk_f32 v151, v153, 0x3a800000, v172
	v_pk_add_f32 v[176:177], v[176:177], v[198:199]
	s_waitcnt lgkmcnt(1)
	v_add_f32_e32 v157, v159, v173
	v_fmamk_f32 v153, v155, 0x3a800000, v172
	v_rsq_f32_e32 v163, v151
	v_add_f32_e32 v151, v176, v177
	v_fmamk_f32 v155, v157, 0x3a800000, v172
	v_rsq_f32_e32 v161, v153
	ds_bpermute_b32 v153, v128, v151
	v_rsq_f32_e32 v159, v155
	s_waitcnt lgkmcnt(1)
	v_add_f32_e32 v155, v165, v174
	v_mov_b32_e32 v176, v203
	v_mov_b32_e32 v177, v204
	v_mov_b32_e32 v203, v205
	v_fmamk_f32 v155, v155, 0x3a800000, v172
	v_pk_add_f32 v[176:177], v[176:177], v[202:203]
	v_rsq_f32_e32 v157, v155
	v_add_f32_e32 v155, v176, v177
	v_mov_b32_e32 v176, v207
	v_mov_b32_e32 v177, v208
	v_mov_b32_e32 v207, v209
	v_pk_add_f32 v[176:177], v[176:177], v[206:207]
	s_waitcnt lgkmcnt(0)
	v_add_f32_e32 v151, v151, v153
	v_add_f32_e32 v173, v176, v177
	ds_bpermute_b32 v153, v149, v151
	ds_bpermute_b32 v165, v128, v155
	ds_bpermute_b32 v128, v128, v173
	v_mul_f32_e32 v174, 0xbfb8aa3b, v175
	v_pk_mul_f32 v[176:177], v[120:121], v[174:175] op_sel_hi:[1,0]
	s_waitcnt lgkmcnt(2)
	v_add_f32_e32 v151, v151, v153
	s_waitcnt lgkmcnt(1)
	v_add_f32_e32 v153, v155, v165
	s_waitcnt lgkmcnt(0)
	v_add_f32_e32 v128, v173, v128
	ds_bpermute_b32 v165, v149, v153
	ds_bpermute_b32 v149, v149, v128
	v_exp_f32_e32 v120, v177
	v_pk_mul_f32 v[178:179], v[122:123], v[174:175] op_sel_hi:[1,0]
	v_fmamk_f32 v151, v151, 0x3a800000, v172
	v_exp_f32_e32 v121, v178
	v_add_f32_e32 v120, 1.0, v120
	s_waitcnt lgkmcnt(0)
; __device__ __forceinline__ unsigned cvt_pk_bf16(float lo, float hi) { unsigned r; asm volatile("v_cvt_pk_bf16_f32 %0, %1, %2" : "=v"(r) : "v"(lo), "v"(hi)); return r; }
; __device__ __forceinline__ float fast_rcp(float x) { return __builtin_amdgcn_rcpf(x); }
; __device__ __forceinline__ unsigned cvt_pk_bf16(float lo, float hi) { const f32x2 v = {lo, hi}; const bf16x2_t b = __builtin_convertvector(v, bf16x2_t); return __builtin_bit_cast(unsigned, b); }
;     __device__ __forceinline__ void operator()(const f32x4 (&acc)[2][2][4][2], const Unit& u, int wr, int wc, int fr, int fq) const {
;     ...
; #pragma unroll
;         for (int ai = 0; ai < 2; ++ai)
; #pragma unroll
;             for (int m = 0; m < 4; ++m) {
;                 const int r = row0 + ai * HALF + m * 16; const float rs = rsv[ai][m], nrs = rs * -1.4426950408889634f, rs2 = rs * rs;
;                 float o[8];
; #pragma unroll
;                 for (int n = 0; n < 2; ++n) {
;                     const f32x4 t = acc[ai][0][m][n] * nrs, p = (acc[ai][0][m][n] * acc[ai][1][m][n]) * rs2;
; #pragma unroll
;                     for (int j = 0; j < 4; ++j) o[4 * n + j] = p[j] * fast_rcp(1.0f + __builtin_amdgcn_exp2f(t[j]));
;                 }
;                 u32x4 w; w.x = cvt_pk_bf16(o[0], o[1]); w.y = cvt_pk_bf16(o[2], o[3]); w.z = cvt_pk_bf16(o[4], o[5]); w.w = cvt_pk_bf16(o[6], o[7]);
;                 *(u32x4*)(O + (size_t)r * ldo + col0) = w;
	v_add_f32_e32 v128, v128, v149
	v_rcp_f32_e32 v149, v120
	v_exp_f32_e32 v120, v179
	v_rsq_f32_e32 v155, v151
	v_add_f32_e32 v151, v153, v165
	v_fmamk_f32 v151, v151, 0x3a800000, v172
	v_fmamk_f32 v128, v128, 0x3a800000, v172
	v_add_f32_e32 v121, 1.0, v121
	v_add_f32_e32 v120, 1.0, v120
	v_rsq_f32_e32 v153, v151
	v_rsq_f32_e32 v151, v128
	v_exp_f32_e32 v128, v176
	v_rcp_f32_e32 v173, v121
	v_rcp_f32_e32 v176, v120
	v_pk_mul_f32 v[120:121], v[116:117], v[174:175] op_sel_hi:[1,0]
	v_mul_f32_e32 v116, v112, v116
	v_exp_f32_e32 v120, v120
	v_exp_f32_e32 v112, v121
	v_pk_mul_f32 v[122:123], v[118:119], v[174:175] op_sel_hi:[1,0]
	v_mul_f32_e32 v117, v113, v117
	v_add_f32_e32 v120, 1.0, v120
	v_add_f32_e32 v112, 1.0, v112
	v_rcp_f32_e32 v120, v120
	v_rcp_f32_e32 v121, v112
	v_mov_b32_e32 v174, v114
	v_mov_b32_e32 v112, v118
	v_mov_b32_e32 v113, v175
	v_pk_mul_f32 v[112:113], v[174:175], v[112:113]
	v_add_f32_e32 v128, 1.0, v128
	v_mul_f32_e32 v116, v116, v113
	v_mul_f32_e32 v117, v117, v113
	v_mul_f32_e32 v120, v116, v120
	v_exp_f32_e32 v116, v122
	v_mul_f32_e32 v121, v117, v121
	v_exp_f32_e32 v117, v123
	v_rcp_f32_e32 v128, v128
	v_add_f32_e32 v116, 1.0, v116
	v_rcp_f32_e32 v116, v116
	v_add_f32_e32 v117, 1.0, v117
	v_rcp_f32_e32 v117, v117
	v_mul_f32_e32 v114, v124, v113
	v_mul_f32_e32 v118, v125, v113
	v_mul_f32_e32 v124, v126, v113
	v_mul_f32_e32 v125, v127, v113
	v_mul_f32_e32 v112, v112, v113
	v_mul_f32_e32 v113, v115, v113
	v_mul_f32_e32 v118, v118, v149
	v_mul_f32_e32 v112, v112, v116
	v_mul_f32_e32 v113, v113, v117
	v_ashrrev_i32_e32 v165, 31, v164
	v_mul_f32_e32 v114, v114, v128
	v_mul_f32_e32 v124, v124, v173
	v_mul_f32_e32 v125, v125, v176
	v_cvt_pk_bf16_f32 v116, v114, v118
	v_cvt_pk_bf16_f32 v117, v124, v125
	v_cvt_pk_bf16_f32 v118, v120, v121
	v_cvt_pk_bf16_f32 v119, v112, v113
	v_mov_b64_e32 v[112:113], s[52:53]
	v_mad_i64_i32 v[120:121], s[4:5], v162, s68, v[112:113]
	v_lshlrev_b64 v[114:115], 1, v[164:165]
	v_lshl_add_u64 v[120:121], v[120:121], 0, v[114:115]
	global_store_dwordx4 v[120:121], v[116:119], off
	v_mov_b32_e32 v162, v98
	s_nop 0
	v_mul_f32_e32 v116, 0xbfb8aa3b, v163
	v_pk_mul_f32 v[118:119], v[108:109], v[116:117] op_sel_hi:[1,0]
	v_mul_f32_e32 v108, v104, v108
	v_exp_f32_e32 v117, v118
	v_exp_f32_e32 v104, v119
	v_mul_f32_e32 v109, v105, v109
	v_pk_mul_f32 v[120:121], v[110:111], v[116:117] op_sel_hi:[1,0]
	v_add_f32_e32 v104, 1.0, v104
	v_add_f32_e32 v117, 1.0, v117
	v_exp_f32_e32 v105, v120
	v_rcp_f32_e32 v118, v104
	v_exp_f32_e32 v104, v121
	v_rcp_f32_e32 v117, v117
	v_add_f32_e32 v105, 1.0, v105
	v_rcp_f32_e32 v119, v105
	v_add_f32_e32 v104, 1.0, v104
	v_rcp_f32_e32 v120, v104
	v_pk_mul_f32 v[104:105], v[100:101], v[116:117] op_sel_hi:[1,0]
	v_mul_f32_e32 v100, v96, v100
	v_exp_f32_e32 v104, v104
	v_exp_f32_e32 v96, v105
	v_mul_f32_e32 v101, v97, v101
	v_mov_b32_e32 v97, v163
	v_add_f32_e32 v104, 1.0, v104
	v_rcp_f32_e32 v104, v104
	v_add_f32_e32 v96, 1.0, v96
	v_rcp_f32_e32 v105, v96
	v_mov_b32_e32 v96, v102
	v_pk_mul_f32 v[96:97], v[162:163], v[96:97]
	v_mul_f32_e32 v110, v106, v110
	v_mul_f32_e32 v111, v107, v111
	v_pk_mul_f32 v[106:107], v[102:103], v[116:117] op_sel_hi:[1,0]
	v_mul_f32_e32 v100, v100, v97
	v_mul_f32_e32 v100, v100, v104
	v_exp_f32_e32 v104, v106
	v_mul_f32_e32 v101, v101, v97
	v_mul_f32_e32 v101, v101, v105
	v_exp_f32_e32 v105, v107
	v_add_f32_e32 v104, 1.0, v104
	v_rcp_f32_e32 v104, v104
	v_mul_f32_e32 v96, v96, v97
	v_add_f32_e32 v105, 1.0, v105
	v_rcp_f32_e32 v105, v105
	v_mul_f32_e32 v98, v108, v97
	v_mul_f32_e32 v104, v96, v104
	v_mul_f32_e32 v96, v99, v103
	v_mul_f32_e32 v98, v98, v117
	v_mul_f32_e32 v102, v109, v97
	v_mul_f32_e32 v108, v110, v97
	v_mul_f32_e32 v109, v111, v97
	v_mul_f32_e32 v96, v96, v97
	v_mul_f32_e32 v102, v102, v118
	v_mul_f32_e32 v108, v108, v119
	v_mul_f32_e32 v109, v109, v120
	v_mul_f32_e32 v99, v96, v105
	v_cvt_pk_bf16_f32 v96, v98, v102
	v_cvt_pk_bf16_f32 v97, v108, v109
	v_cvt_pk_bf16_f32 v98, v100, v101
	v_mad_i64_i32 v[100:101], s[4:5], v160, s68, v[112:113]
	v_lshl_add_u64 v[100:101], v[100:101], 0, v[114:115]
	v_cvt_pk_bf16_f32 v99, v104, v99
	global_store_dwordx4 v[100:101], v[96:99], off
	v_mov_b32_e32 v160, v82
	s_nop 0
	v_mul_f32_e32 v96, 0xbfb8aa3b, v161
	v_pk_mul_f32 v[98:99], v[92:93], v[96:97] op_sel_hi:[1,0]
	v_mul_f32_e32 v92, v88, v92
	v_exp_f32_e32 v97, v98
	v_exp_f32_e32 v88, v99
	v_mul_f32_e32 v93, v89, v93
	v_pk_mul_f32 v[100:101], v[94:95], v[96:97] op_sel_hi:[1,0]
	v_add_f32_e32 v88, 1.0, v88
	v_add_f32_e32 v97, 1.0, v97
	v_exp_f32_e32 v89, v100
	v_rcp_f32_e32 v98, v88
	v_exp_f32_e32 v88, v101
	v_rcp_f32_e32 v97, v97
	v_add_f32_e32 v89, 1.0, v89
	v_rcp_f32_e32 v99, v89
	v_add_f32_e32 v88, 1.0, v88
	v_rcp_f32_e32 v100, v88
	v_pk_mul_f32 v[88:89], v[84:85], v[96:97] op_sel_hi:[1,0]
	v_mul_f32_e32 v84, v80, v84
	v_exp_f32_e32 v88, v88
	v_exp_f32_e32 v80, v89
	v_mul_f32_e32 v85, v81, v85
	v_mov_b32_e32 v81, v161
	v_add_f32_e32 v88, 1.0, v88
	v_rcp_f32_e32 v88, v88
	v_add_f32_e32 v80, 1.0, v80
	v_rcp_f32_e32 v89, v80
	v_mov_b32_e32 v80, v86
	v_pk_mul_f32 v[80:81], v[160:161], v[80:81]
	v_mul_f32_e32 v94, v90, v94
	v_mul_f32_e32 v95, v91, v95
	v_pk_mul_f32 v[90:91], v[86:87], v[96:97] op_sel_hi:[1,0]
	v_mul_f32_e32 v84, v84, v81
	v_mul_f32_e32 v84, v84, v88
	v_exp_f32_e32 v88, v90
	v_mul_f32_e32 v85, v85, v81
	v_mul_f32_e32 v85, v85, v89
	v_exp_f32_e32 v89, v91
	v_add_f32_e32 v88, 1.0, v88
	v_rcp_f32_e32 v88, v88
	v_mul_f32_e32 v80, v80, v81
	v_add_f32_e32 v89, 1.0, v89
	v_rcp_f32_e32 v89, v89
	v_mul_f32_e32 v82, v92, v81
	v_mul_f32_e32 v88, v80, v88
	v_mul_f32_e32 v80, v83, v87
	v_mul_f32_e32 v82, v82, v97
	v_mul_f32_e32 v86, v93, v81
; __device__ __forceinline__ unsigned cvt_pk_bf16(float lo, float hi) { unsigned r; asm volatile("v_cvt_pk_bf16_f32 %0, %1, %2" : "=v"(r) : "v"(lo), "v"(hi)); return r; }
; __device__ __forceinline__ float fast_rcp(float x) { return __builtin_amdgcn_rcpf(x); }
; __device__ __forceinline__ unsigned cvt_pk_bf16(float lo, float hi) { const f32x2 v = {lo, hi}; const bf16x2_t b = __builtin_convertvector(v, bf16x2_t); return __builtin_bit_cast(unsigned, b); }
;     __device__ __forceinline__ void operator()(const f32x4 (&acc)[2][2][4][2], const Unit& u, int wr, int wc, int fr, int fq) const {
;     ...
; #pragma unroll
;         for (int ai = 0; ai < 2; ++ai)
; #pragma unroll
;             for (int m = 0; m < 4; ++m) {
;                 const int r = row0 + ai * HALF + m * 16; const float rs = rsv[ai][m], nrs = rs * -1.4426950408889634f, rs2 = rs * rs;
;                 float o[8];
; #pragma unroll
;                 for (int n = 0; n < 2; ++n) {
;                     const f32x4 t = acc[ai][0][m][n] * nrs, p = (acc[ai][0][m][n] * acc[ai][1][m][n]) * rs2;
; #pragma unroll
;                     for (int j = 0; j < 4; ++j) o[4 * n + j] = p[j] * fast_rcp(1.0f + __builtin_amdgcn_exp2f(t[j]));
;                 }
;                 u32x4 w; w.x = cvt_pk_bf16(o[0], o[1]); w.y = cvt_pk_bf16(o[2], o[3]); w.z = cvt_pk_bf16(o[4], o[5]); w.w = cvt_pk_bf16(o[6], o[7]);
;                 *(u32x4*)(O + (size_t)r * ldo + col0) = w;
	v_mul_f32_e32 v92, v94, v81
	v_mul_f32_e32 v93, v95, v81
	v_mul_f32_e32 v80, v80, v81
	v_mul_f32_e32 v86, v86, v98
	v_mul_f32_e32 v92, v92, v99
	v_mul_f32_e32 v93, v93, v100
	v_mul_f32_e32 v83, v80, v89
	v_cvt_pk_bf16_f32 v80, v82, v86
	v_cvt_pk_bf16_f32 v81, v92, v93
	v_cvt_pk_bf16_f32 v82, v84, v85
	v_mad_i64_i32 v[84:85], s[4:5], v158, s68, v[112:113]
	v_lshl_add_u64 v[84:85], v[84:85], 0, v[114:115]
	v_cvt_pk_bf16_f32 v83, v88, v83
	global_store_dwordx4 v[84:85], v[80:83], off
	v_mov_b32_e32 v158, v66
	s_nop 0
	v_mul_f32_e32 v80, 0xbfb8aa3b, v159
	v_pk_mul_f32 v[82:83], v[76:77], v[80:81] op_sel_hi:[1,0]
	v_mul_f32_e32 v76, v72, v76
	v_exp_f32_e32 v81, v82
	v_exp_f32_e32 v72, v83
	v_mul_f32_e32 v77, v73, v77
	v_pk_mul_f32 v[84:85], v[78:79], v[80:81] op_sel_hi:[1,0]
	v_add_f32_e32 v72, 1.0, v72
	v_add_f32_e32 v81, 1.0, v81
	v_exp_f32_e32 v73, v84
	v_rcp_f32_e32 v82, v72
	v_exp_f32_e32 v72, v85
	v_rcp_f32_e32 v81, v81
	v_add_f32_e32 v73, 1.0, v73
	v_rcp_f32_e32 v83, v73
	v_add_f32_e32 v72, 1.0, v72
	v_rcp_f32_e32 v84, v72
	v_pk_mul_f32 v[72:73], v[68:69], v[80:81] op_sel_hi:[1,0]
	v_mul_f32_e32 v68, v64, v68
	v_exp_f32_e32 v72, v72
	v_exp_f32_e32 v64, v73
	v_mul_f32_e32 v69, v65, v69
	v_mov_b32_e32 v65, v159
	v_add_f32_e32 v72, 1.0, v72
	v_rcp_f32_e32 v72, v72
	v_add_f32_e32 v64, 1.0, v64
	v_rcp_f32_e32 v73, v64
	v_mov_b32_e32 v64, v70
	v_pk_mul_f32 v[64:65], v[158:159], v[64:65]
	v_mul_f32_e32 v78, v74, v78
	v_mul_f32_e32 v79, v75, v79
	v_pk_mul_f32 v[74:75], v[70:71], v[80:81] op_sel_hi:[1,0]
	v_mul_f32_e32 v68, v68, v65
	v_mul_f32_e32 v68, v68, v72
	v_exp_f32_e32 v72, v74
	v_mul_f32_e32 v69, v69, v65
	v_mul_f32_e32 v69, v69, v73
	v_exp_f32_e32 v73, v75
	v_add_f32_e32 v72, 1.0, v72
	v_rcp_f32_e32 v72, v72
	v_mul_f32_e32 v64, v64, v65
	v_add_f32_e32 v73, 1.0, v73
	v_rcp_f32_e32 v73, v73
	v_mul_f32_e32 v66, v76, v65
	v_mul_f32_e32 v72, v64, v72
	v_mul_f32_e32 v64, v67, v71
	v_mul_f32_e32 v66, v66, v81
	v_mul_f32_e32 v70, v77, v65
	v_mul_f32_e32 v76, v78, v65
	v_mul_f32_e32 v77, v79, v65
	v_mul_f32_e32 v64, v64, v65
	v_mul_f32_e32 v70, v70, v82
	v_mul_f32_e32 v76, v76, v83
	v_mul_f32_e32 v77, v77, v84
	v_mul_f32_e32 v67, v64, v73
	v_cvt_pk_bf16_f32 v64, v66, v70
	v_cvt_pk_bf16_f32 v65, v76, v77
	v_cvt_pk_bf16_f32 v66, v68, v69
	v_mad_i64_i32 v[68:69], s[4:5], v156, s68, v[112:113]
	v_lshl_add_u64 v[68:69], v[68:69], 0, v[114:115]
	v_cvt_pk_bf16_f32 v67, v72, v67
	global_store_dwordx4 v[68:69], v[64:67], off
	v_mov_b32_e32 v156, v50
	s_nop 0
	v_mul_f32_e32 v64, 0xbfb8aa3b, v157
	v_pk_mul_f32 v[66:67], v[60:61], v[64:65] op_sel_hi:[1,0]
	v_mul_f32_e32 v60, v56, v60
	v_exp_f32_e32 v65, v66
	v_exp_f32_e32 v56, v67
	v_mul_f32_e32 v61, v57, v61
	v_pk_mul_f32 v[68:69], v[62:63], v[64:65] op_sel_hi:[1,0]
	v_add_f32_e32 v56, 1.0, v56
	v_add_f32_e32 v65, 1.0, v65
	v_exp_f32_e32 v57, v68
	v_rcp_f32_e32 v66, v56
	v_exp_f32_e32 v56, v69
	v_rcp_f32_e32 v65, v65
	v_add_f32_e32 v57, 1.0, v57
	v_rcp_f32_e32 v67, v57
	v_add_f32_e32 v56, 1.0, v56
	v_rcp_f32_e32 v68, v56
	v_pk_mul_f32 v[56:57], v[52:53], v[64:65] op_sel_hi:[1,0]
	v_mul_f32_e32 v52, v48, v52
	v_exp_f32_e32 v56, v56
	v_exp_f32_e32 v48, v57
	v_mul_f32_e32 v53, v49, v53
	v_mov_b32_e32 v49, v157
	v_add_f32_e32 v56, 1.0, v56
	v_rcp_f32_e32 v56, v56
	v_add_f32_e32 v48, 1.0, v48
	v_rcp_f32_e32 v57, v48
	v_mov_b32_e32 v48, v54
	v_pk_mul_f32 v[48:49], v[156:157], v[48:49]
	v_mul_f32_e32 v62, v58, v62
	v_mul_f32_e32 v63, v59, v63
	v_pk_mul_f32 v[58:59], v[54:55], v[64:65] op_sel_hi:[1,0]
	v_mul_f32_e32 v52, v52, v49
	v_mul_f32_e32 v52, v52, v56
	v_exp_f32_e32 v56, v58
	v_mul_f32_e32 v53, v53, v49
	v_mul_f32_e32 v53, v53, v57
	v_exp_f32_e32 v57, v59
	v_add_f32_e32 v56, 1.0, v56
	v_rcp_f32_e32 v56, v56
	v_mul_f32_e32 v48, v48, v49
	v_add_f32_e32 v57, 1.0, v57
	v_rcp_f32_e32 v57, v57
	v_mul_f32_e32 v50, v60, v49
	v_mul_f32_e32 v56, v48, v56
	v_mul_f32_e32 v48, v51, v55
	v_mul_f32_e32 v50, v50, v65
	v_mul_f32_e32 v54, v61, v49
	v_mul_f32_e32 v60, v62, v49
	v_mul_f32_e32 v61, v63, v49
	v_mul_f32_e32 v48, v48, v49
	v_mul_f32_e32 v54, v54, v66
	v_mul_f32_e32 v60, v60, v67
	v_mul_f32_e32 v61, v61, v68
	v_mul_f32_e32 v51, v48, v57
	v_cvt_pk_bf16_f32 v48, v50, v54
	v_cvt_pk_bf16_f32 v49, v60, v61
	v_cvt_pk_bf16_f32 v50, v52, v53
	v_mad_i64_i32 v[52:53], s[4:5], v154, s68, v[112:113]
	v_lshl_add_u64 v[52:53], v[52:53], 0, v[114:115]
	v_cvt_pk_bf16_f32 v51, v56, v51
	global_store_dwordx4 v[52:53], v[48:51], off
	v_mov_b32_e32 v154, v34
	s_nop 0
	v_mul_f32_e32 v48, 0xbfb8aa3b, v155
	v_pk_mul_f32 v[50:51], v[44:45], v[48:49] op_sel_hi:[1,0]
	v_mul_f32_e32 v44, v40, v44
	v_exp_f32_e32 v49, v50
	v_exp_f32_e32 v40, v51
	v_mul_f32_e32 v45, v41, v45
	v_pk_mul_f32 v[52:53], v[46:47], v[48:49] op_sel_hi:[1,0]
	v_add_f32_e32 v40, 1.0, v40
	v_add_f32_e32 v49, 1.0, v49
	v_exp_f32_e32 v41, v52
	v_rcp_f32_e32 v50, v40
	v_exp_f32_e32 v40, v53
	v_rcp_f32_e32 v49, v49
	v_add_f32_e32 v41, 1.0, v41
	v_rcp_f32_e32 v51, v41
	v_add_f32_e32 v40, 1.0, v40
	v_rcp_f32_e32 v52, v40
	v_pk_mul_f32 v[40:41], v[36:37], v[48:49] op_sel_hi:[1,0]
	v_mul_f32_e32 v36, v32, v36
	v_exp_f32_e32 v40, v40
	v_exp_f32_e32 v32, v41
	v_mul_f32_e32 v37, v33, v37
	v_mov_b32_e32 v33, v155
; __device__ __forceinline__ unsigned cvt_pk_bf16(float lo, float hi) { unsigned r; asm volatile("v_cvt_pk_bf16_f32 %0, %1, %2" : "=v"(r) : "v"(lo), "v"(hi)); return r; }
; __device__ __forceinline__ float fast_rcp(float x) { return __builtin_amdgcn_rcpf(x); }
; #define PG8_BAR __builtin_amdgcn_s_barrier()
; __device__ __forceinline__ unsigned cvt_pk_bf16(float lo, float hi) { const f32x2 v = {lo, hi}; const bf16x2_t b = __builtin_convertvector(v, bf16x2_t); return __builtin_bit_cast(unsigned, b); }
;     __device__ __forceinline__ void operator()(const f32x4 (&acc)[2][2][4][2], const Unit& u, int wr, int wc, int fr, int fq) const {
;     ...
; #pragma unroll
;         for (int ai = 0; ai < 2; ++ai)
; #pragma unroll
;             for (int m = 0; m < 4; ++m) {
;                 const int r = row0 + ai * HALF + m * 16; const float rs = rsv[ai][m], nrs = rs * -1.4426950408889634f, rs2 = rs * rs;
;                 float o[8];
; #pragma unroll
;                 for (int n = 0; n < 2; ++n) {
;                     const f32x4 t = acc[ai][0][m][n] * nrs, p = (acc[ai][0][m][n] * acc[ai][1][m][n]) * rs2;
; #pragma unroll
;                     for (int j = 0; j < 4; ++j) o[4 * n + j] = p[j] * fast_rcp(1.0f + __builtin_amdgcn_exp2f(t[j]));
;                 }
;                 u32x4 w; w.x = cvt_pk_bf16(o[0], o[1]); w.y = cvt_pk_bf16(o[2], o[3]); w.z = cvt_pk_bf16(o[4], o[5]); w.w = cvt_pk_bf16(o[6], o[7]);
;                 *(u32x4*)(O + (size_t)r * ldo + col0) = w;
; template <class Epi, class Sched, bool ALIGN_EPI = false, bool SP2 = false>
; __device__ __forceinline__ void gemm_phase(PG8_LAS unsigned char* lds, const Gemm g, const Sched& S, const Epi& E) {
;     ...
;         if (!has_next) break;
; #pragma unroll
;         for (int a = 0; a < 2; ++a)
; #pragma unroll
;             for (int b = 0; b < 2; ++b)
; #pragma unroll
;                 for (int m = 0; m < 4; ++m)
; #pragma unroll
;                     for (int n = 0; n < 2; ++n) acc[a][b][m][n] = (f32x4){0.f, 0.f, 0.f, 0.f};
;         cur = nxt; cA = nA; cB = nB; ++ui;
;         if constexpr (ALIGN_EPI) { if (wr == 1) PG8_BAR; }
	v_add_f32_e32 v40, 1.0, v40
	v_rcp_f32_e32 v40, v40
	v_add_f32_e32 v32, 1.0, v32
	v_rcp_f32_e32 v41, v32
	v_mov_b32_e32 v32, v38
	v_pk_mul_f32 v[32:33], v[154:155], v[32:33]
	v_mul_f32_e32 v46, v42, v46
	v_mul_f32_e32 v47, v43, v47
	v_pk_mul_f32 v[42:43], v[38:39], v[48:49] op_sel_hi:[1,0]
	v_mul_f32_e32 v36, v36, v33
	v_mul_f32_e32 v36, v36, v40
	v_exp_f32_e32 v40, v42
	v_mul_f32_e32 v37, v37, v33
	v_mul_f32_e32 v37, v37, v41
	v_exp_f32_e32 v41, v43
	v_add_f32_e32 v40, 1.0, v40
	v_rcp_f32_e32 v40, v40
	v_mul_f32_e32 v32, v32, v33
	v_add_f32_e32 v41, 1.0, v41
	v_rcp_f32_e32 v41, v41
	v_mul_f32_e32 v34, v44, v33
	v_mul_f32_e32 v40, v32, v40
	v_mul_f32_e32 v32, v35, v39
	v_mul_f32_e32 v34, v34, v49
	v_mul_f32_e32 v38, v45, v33
	v_mul_f32_e32 v44, v46, v33
	v_mul_f32_e32 v45, v47, v33
	v_mul_f32_e32 v32, v32, v33
	v_mul_f32_e32 v38, v38, v50
	v_mul_f32_e32 v44, v44, v51
	v_mul_f32_e32 v45, v45, v52
	v_mul_f32_e32 v35, v32, v41
	v_cvt_pk_bf16_f32 v32, v34, v38
	v_cvt_pk_bf16_f32 v33, v44, v45
	v_cvt_pk_bf16_f32 v34, v36, v37
	v_mad_i64_i32 v[36:37], s[4:5], v152, s68, v[112:113]
	v_lshl_add_u64 v[36:37], v[36:37], 0, v[114:115]
	v_cvt_pk_bf16_f32 v35, v40, v35
	global_store_dwordx4 v[36:37], v[32:35], off
	v_mov_b32_e32 v152, v18
	s_nop 0
	v_mul_f32_e32 v32, 0xbfb8aa3b, v153
	v_pk_mul_f32 v[34:35], v[28:29], v[32:33] op_sel_hi:[1,0]
	v_mul_f32_e32 v28, v24, v28
	v_exp_f32_e32 v33, v34
	v_exp_f32_e32 v24, v35
	v_mul_f32_e32 v29, v25, v29
	v_pk_mul_f32 v[36:37], v[30:31], v[32:33] op_sel_hi:[1,0]
	v_add_f32_e32 v24, 1.0, v24
	v_add_f32_e32 v33, 1.0, v33
	v_exp_f32_e32 v25, v36
	v_rcp_f32_e32 v34, v24
	v_exp_f32_e32 v24, v37
	v_rcp_f32_e32 v33, v33
	v_add_f32_e32 v25, 1.0, v25
	v_rcp_f32_e32 v35, v25
	v_add_f32_e32 v24, 1.0, v24
	v_rcp_f32_e32 v36, v24
	v_pk_mul_f32 v[24:25], v[20:21], v[32:33] op_sel_hi:[1,0]
	v_mul_f32_e32 v20, v16, v20
	v_exp_f32_e32 v24, v24
	v_exp_f32_e32 v16, v25
	v_mul_f32_e32 v21, v17, v21
	v_mov_b32_e32 v17, v153
	v_add_f32_e32 v24, 1.0, v24
	v_rcp_f32_e32 v24, v24
	v_add_f32_e32 v16, 1.0, v16
	v_rcp_f32_e32 v25, v16
	v_mov_b32_e32 v16, v22
	v_pk_mul_f32 v[16:17], v[152:153], v[16:17]
	v_mul_f32_e32 v30, v26, v30
	v_mul_f32_e32 v31, v27, v31
	v_pk_mul_f32 v[26:27], v[22:23], v[32:33] op_sel_hi:[1,0]
	v_mul_f32_e32 v20, v20, v17
	v_mul_f32_e32 v20, v20, v24
	v_exp_f32_e32 v24, v26
	v_mul_f32_e32 v21, v21, v17
	v_mul_f32_e32 v21, v21, v25
	v_exp_f32_e32 v25, v27
	v_add_f32_e32 v24, 1.0, v24
	v_rcp_f32_e32 v24, v24
	v_mul_f32_e32 v16, v16, v17
	v_add_f32_e32 v25, 1.0, v25
	v_rcp_f32_e32 v25, v25
	v_mul_f32_e32 v18, v28, v17
	v_mul_f32_e32 v24, v16, v24
	v_mul_f32_e32 v16, v19, v23
	v_mul_f32_e32 v18, v18, v33
	v_mul_f32_e32 v22, v29, v17
	v_mul_f32_e32 v28, v30, v17
	v_mul_f32_e32 v29, v31, v17
	v_mul_f32_e32 v16, v16, v17
	v_mul_f32_e32 v22, v22, v34
	v_mul_f32_e32 v28, v28, v35
	v_mul_f32_e32 v29, v29, v36
	v_mul_f32_e32 v19, v16, v25
	v_cvt_pk_bf16_f32 v16, v18, v22
	v_cvt_pk_bf16_f32 v17, v28, v29
	v_cvt_pk_bf16_f32 v18, v20, v21
	v_mad_i64_i32 v[20:21], s[4:5], v150, s68, v[112:113]
	v_lshl_add_u64 v[20:21], v[20:21], 0, v[114:115]
	v_cvt_pk_bf16_f32 v19, v24, v19
	global_store_dwordx4 v[20:21], v[16:19], off
	v_mov_b32_e32 v150, v2
	s_nop 0
	v_mul_f32_e32 v16, 0xbfb8aa3b, v151
	v_pk_mul_f32 v[18:19], v[12:13], v[16:17] op_sel_hi:[1,0]
	v_mul_f32_e32 v12, v8, v12
	v_exp_f32_e32 v17, v18
	v_exp_f32_e32 v8, v19
	v_mul_f32_e32 v13, v9, v13
	v_pk_mul_f32 v[20:21], v[14:15], v[16:17] op_sel_hi:[1,0]
	v_add_f32_e32 v8, 1.0, v8
	v_add_f32_e32 v17, 1.0, v17
	v_exp_f32_e32 v9, v20
	v_rcp_f32_e32 v18, v8
	v_exp_f32_e32 v8, v21
	v_rcp_f32_e32 v17, v17
	v_add_f32_e32 v9, 1.0, v9
	v_rcp_f32_e32 v19, v9
	v_add_f32_e32 v8, 1.0, v8
	v_rcp_f32_e32 v20, v8
	v_pk_mul_f32 v[8:9], v[4:5], v[16:17] op_sel_hi:[1,0]
	v_mul_f32_e32 v4, v0, v4
	v_exp_f32_e32 v8, v8
	v_exp_f32_e32 v0, v9
	v_mul_f32_e32 v5, v1, v5
	v_mov_b32_e32 v1, v151
	v_add_f32_e32 v8, 1.0, v8
	v_rcp_f32_e32 v8, v8
	v_add_f32_e32 v0, 1.0, v0
	v_rcp_f32_e32 v9, v0
	v_mov_b32_e32 v0, v6
	v_pk_mul_f32 v[0:1], v[150:151], v[0:1]
	v_mul_f32_e32 v14, v10, v14
	v_mul_f32_e32 v15, v11, v15
	v_pk_mul_f32 v[10:11], v[6:7], v[16:17] op_sel_hi:[1,0]
	v_mul_f32_e32 v4, v4, v1
	v_mul_f32_e32 v4, v4, v8
	v_exp_f32_e32 v8, v10
	v_mul_f32_e32 v5, v5, v1
	v_mul_f32_e32 v5, v5, v9
	v_exp_f32_e32 v9, v11
	v_add_f32_e32 v8, 1.0, v8
	v_rcp_f32_e32 v8, v8
	v_mul_f32_e32 v0, v0, v1
	v_add_f32_e32 v9, 1.0, v9
	v_rcp_f32_e32 v9, v9
	v_mul_f32_e32 v2, v12, v1
	v_mul_f32_e32 v8, v0, v8
	v_mul_f32_e32 v0, v3, v7
	v_mul_f32_e32 v2, v2, v17
	v_mul_f32_e32 v6, v13, v1
	v_mul_f32_e32 v12, v14, v1
	v_mul_f32_e32 v13, v15, v1
	v_mul_f32_e32 v0, v0, v1
	v_mul_f32_e32 v6, v6, v18
	v_mul_f32_e32 v12, v12, v19
	v_mul_f32_e32 v13, v13, v20
	v_mul_f32_e32 v3, v0, v9
	v_cvt_pk_bf16_f32 v0, v2, v6
	v_cvt_pk_bf16_f32 v1, v12, v13
	v_cvt_pk_bf16_f32 v2, v4, v5
	v_mad_i64_i32 v[4:5], s[4:5], v148, s68, v[112:113]
	v_lshl_add_u64 v[4:5], v[4:5], 0, v[114:115]
	v_cvt_pk_bf16_f32 v3, v8, v3
	global_store_dwordx4 v[4:5], v[0:3], off
	s_cbranch_vccnz .LBB0_255
	s_andn2_b64 vcc, exec, s[16:17]
	s_cbranch_vccnz .LBB0_254
	s_barrier
	s_branch .LBB0_254
